# O2: second-round items assigned to even workgroups instead of workgroups 0-127
# baseline (speedup 1.0000x reference)
.LBB0_540:
	s_or_b64 exec, exec, s[46:47]
	s_barrier
	s_cmpk_gt_i32 s7, 0xff
	s_cbranch_scc1 .LBB0_562
	s_bitcmp1_b32 s7, 0
	s_cbranch_scc1 .LBB0_562
	s_lshr_b32 s7, s7, 1
	s_addk_i32 s7, 0x100
	s_lshl_b32 s3, s7, 4
